# lever 1 in all post-phase row loops: parameter waits no longer drain the next row's prefetch; next-row data waited at its consumer (counted past the row's stores)
# baseline (speedup 1.0000x reference)
.LBB0_827:
	s_or_b64 exec, exec, s[28:29]
	v_lshlrev_b32_e32 v156, 16, v108
	v_and_b32_e32 v157, 0xffff0000, v108
	v_lshlrev_b32_e32 v108, 16, v109
	v_and_b32_e32 v109, 0xffff0000, v109
	v_pk_mul_f32 v[164:165], v[156:157], v[156:157]
	v_pk_mul_f32 v[166:167], v[108:109], v[108:109]
	v_add_f32_e32 v164, v164, v165
	v_lshlrev_b32_e32 v158, 16, v110
	v_and_b32_e32 v159, 0xffff0000, v110
	v_add_f32_e32 v164, v166, v164
	v_pk_mul_f32 v[168:169], v[158:159], v[158:159]
	v_add_f32_e32 v164, v167, v164
	v_lshlrev_b32_e32 v110, 16, v111
	v_and_b32_e32 v111, 0xffff0000, v111
	v_add_f32_e32 v164, v168, v164
	v_pk_mul_f32 v[170:171], v[110:111], v[110:111]
	v_add_f32_e32 v164, v169, v164
	v_lshlrev_b32_e32 v160, 16, v96
	v_and_b32_e32 v161, 0xffff0000, v96
	v_add_f32_e32 v164, v170, v164
	v_pk_mul_f32 v[172:173], v[160:161], v[160:161]
	v_add_f32_e32 v164, v171, v164
	v_lshlrev_b32_e32 v96, 16, v97
	v_and_b32_e32 v97, 0xffff0000, v97
	v_add_f32_e32 v164, v172, v164
	v_pk_mul_f32 v[174:175], v[96:97], v[96:97]
	v_add_f32_e32 v164, v173, v164
	v_lshlrev_b32_e32 v162, 16, v98
	v_and_b32_e32 v163, 0xffff0000, v98
	v_add_f32_e32 v164, v174, v164
	v_pk_mul_f32 v[176:177], v[162:163], v[162:163]
	v_add_f32_e32 v164, v175, v164
	v_lshlrev_b32_e32 v98, 16, v99
	v_and_b32_e32 v99, 0xffff0000, v99
	v_add_f32_e32 v164, v176, v164
	v_pk_mul_f32 v[178:179], v[98:99], v[98:99]
	v_add_f32_e32 v164, v177, v164
	v_add_f32_e32 v164, v178, v164
	v_add_f32_e32 v164, v179, v164
	ds_bpermute_b32 v165, v147, v164
	s_and_b64 s[2:3], exec, s[2:3]
	s_or_b64 s[18:19], s[2:3], s[18:19]
	v_lshl_add_u64 v[122:123], v[122:123], 0, s[26:27]
	v_lshl_add_u64 v[126:127], v[126:127], 0, s[24:25]
	s_waitcnt lgkmcnt(0)
	v_add_f32_e32 v164, v164, v165
	ds_bpermute_b32 v165, v148, v164
	s_waitcnt lgkmcnt(0)
	v_add_f32_e32 v164, v164, v165
	ds_bpermute_b32 v165, v149, v164
	s_waitcnt lgkmcnt(0)
	v_add_f32_e32 v164, v164, v165
	ds_bpermute_b32 v165, v150, v164
	s_waitcnt lgkmcnt(0)
	v_add_f32_e32 v164, v164, v165
	ds_bpermute_b32 v165, v151, v164
	s_waitcnt lgkmcnt(0)
	v_add_f32_e32 v164, v164, v165
	ds_bpermute_b32 v165, v152, v164
	s_waitcnt lgkmcnt(0)
	v_add_f32_e32 v164, v164, v165
	v_fmamk_f32 v164, v164, 0x3a800000, v155
	v_mul_f32_e32 v165, 0x4b800000, v164
	v_cmp_gt_f32_e32 vcc, s35, v164
	s_nop 1
	v_cndmask_b32_e32 v164, v164, v165, vcc
	v_rsq_f32_e32 v164, v164
	s_nop 0
	v_mul_f32_e32 v165, 0x45800000, v164
	v_cndmask_b32_e32 v164, v164, v165, vcc
	v_pk_mul_f32 v[96:97], v[164:165], v[96:97] op_sel_hi:[0,1]
	v_pk_mul_f32 v[96:97], v[10:11], v[96:97]
	v_pk_mul_f32 v[108:109], v[164:165], v[108:109] op_sel_hi:[0,1]
	s_nop 0
	v_pk_fma_f32 v[38:39], v[94:95], v[96:97], v[38:39]
	v_pk_mul_f32 v[96:97], v[164:165], v[162:163] op_sel_hi:[0,1]
	v_pk_mul_f32 v[156:157], v[164:165], v[156:157] op_sel_hi:[0,1]
	v_pk_mul_f32 v[158:159], v[164:165], v[158:159] op_sel_hi:[0,1]
	v_pk_mul_f32 v[108:109], v[26:27], v[108:109]
	v_pk_mul_f32 v[96:97], v[12:13], v[96:97]
	v_pk_mul_f32 v[156:157], v[24:25], v[156:157]
	v_pk_fma_f32 v[46:47], v[50:51], v[108:109], v[46:47]
	v_pk_mul_f32 v[108:109], v[28:29], v[158:159]
	s_nop 0
	v_pk_fma_f32 v[32:33], v[88:89], v[96:97], v[32:33]
	v_pk_mul_f32 v[96:97], v[164:165], v[98:99] op_sel_hi:[0,1]
	v_pk_fma_f32 v[44:45], v[48:49], v[156:157], v[44:45]
	v_pk_fma_f32 v[40:41], v[52:53], v[108:109], v[40:41]
	v_pk_mul_f32 v[108:109], v[164:165], v[110:111] op_sel_hi:[0,1]
	v_pk_mul_f32 v[96:97], v[14:15], v[96:97]
	v_pk_mul_f32 v[108:109], v[30:31], v[108:109]
	v_pk_fma_f32 v[34:35], v[90:91], v[96:97], v[34:35]
	v_pk_mul_f32 v[96:97], v[44:45], v[44:45]
	v_pk_fma_f32 v[42:43], v[54:55], v[108:109], v[42:43]
	v_pk_mul_f32 v[108:109], v[164:165], v[160:161] op_sel_hi:[0,1]
	v_pk_mul_f32 v[98:99], v[46:47], v[46:47]
	v_add_f32_e32 v96, v96, v97
	v_pk_mul_f32 v[108:109], v[8:9], v[108:109]
	v_add_f32_e32 v96, v98, v96
	v_pk_fma_f32 v[36:37], v[92:93], v[108:109], v[36:37]
	v_pk_mul_f32 v[108:109], v[40:41], v[40:41]
	v_add_f32_e32 v96, v99, v96
	v_add_f32_e32 v96, v108, v96
	v_pk_mul_f32 v[110:111], v[42:43], v[42:43]
	v_add_f32_e32 v96, v109, v96
	v_add_f32_e32 v96, v110, v96
	v_pk_mul_f32 v[156:157], v[36:37], v[36:37]
	v_add_f32_e32 v96, v111, v96
	v_add_f32_e32 v96, v156, v96
	v_pk_mul_f32 v[158:159], v[38:39], v[38:39]
	v_add_f32_e32 v96, v157, v96
	v_add_f32_e32 v96, v158, v96
	v_pk_mul_f32 v[160:161], v[32:33], v[32:33]
	v_add_f32_e32 v96, v159, v96
	v_add_f32_e32 v96, v160, v96
	v_pk_mul_f32 v[162:163], v[34:35], v[34:35]
	v_add_f32_e32 v96, v161, v96
	v_add_f32_e32 v96, v162, v96
	v_add_f32_e32 v96, v163, v96
	ds_bpermute_b32 v97, v147, v96
	s_waitcnt lgkmcnt(0)
	v_add_f32_e32 v96, v96, v97
	ds_bpermute_b32 v97, v148, v96
	s_waitcnt lgkmcnt(0)
	v_add_f32_e32 v96, v96, v97
	ds_bpermute_b32 v97, v149, v96
	s_waitcnt lgkmcnt(0)
	v_add_f32_e32 v96, v96, v97
	ds_bpermute_b32 v97, v150, v96
	s_waitcnt lgkmcnt(0)
	v_add_f32_e32 v96, v96, v97
	ds_bpermute_b32 v97, v151, v96
	s_waitcnt lgkmcnt(0)
	v_add_f32_e32 v98, v96, v97
	ds_bpermute_b32 v99, v152, v98
	v_lshl_add_u64 v[96:97], v[124:125], 0, v[120:121]
	global_store_dwordx4 v[96:97], v[44:47], off
	global_store_dwordx4 v[96:97], v[40:43], off offset:16
	global_store_dwordx4 v[96:97], v[36:39], off offset:2048
	global_store_dwordx4 v[96:97], v[32:35], off offset:2064
	v_lshl_add_u64 v[124:125], v[124:125], 0, s[26:27]
	s_waitcnt lgkmcnt(0)
	v_add_f32_e32 v98, v98, v99
	v_fmamk_f32 v98, v98, 0x3a800000, v155
	v_mul_f32_e32 v99, 0x4b800000, v98
	v_cmp_gt_f32_e32 vcc, s35, v98
	s_nop 1
	v_cndmask_b32_e32 v98, v98, v99, vcc
	v_rsq_f32_e32 v98, v98
	s_nop 0
	v_mul_f32_e32 v96, 0x45800000, v98
	v_cndmask_b32_e32 v96, v98, v96, vcc
	v_pk_mul_f32 v[40:41], v[40:41], v[96:97] op_sel_hi:[1,0]
	v_pk_mul_f32 v[44:45], v[44:45], v[96:97] op_sel_hi:[1,0]
	v_pk_mul_f32 v[40:41], v[20:21], v[40:41]
	v_pk_mul_f32 v[44:45], v[16:17], v[44:45]
	v_pk_fma_f32 v[98:99], v[134:135], v[40:41], v[68:69]
	v_pk_mul_f32 v[40:41], v[42:43], v[96:97] op_sel_hi:[1,0]
	v_pk_fma_f32 v[44:45], v[138:139], v[44:45], v[64:65]
	v_pk_mul_f32 v[46:47], v[46:47], v[96:97] op_sel_hi:[1,0]
	v_pk_mul_f32 v[40:41], v[22:23], v[40:41]
	v_pk_mul_f32 v[46:47], v[18:19], v[46:47]
	v_pk_fma_f32 v[108:109], v[132:133], v[40:41], v[70:71]
	v_cvt_pk_bf16_f32 v40, v44, v45
	v_lshl_add_u64 v[44:45], v[114:115], 0, v[118:119]
	v_pk_fma_f32 v[46:47], v[136:137], v[46:47], v[66:67]
	v_add_co_u32_e32 v44, vcc, s36, v44
	v_pk_mul_f32 v[32:33], v[32:33], v[96:97] op_sel_hi:[1,0]
	v_cvt_pk_bf16_f32 v41, v46, v47
	v_cvt_pk_bf16_f32 v42, v98, v99
	v_cvt_pk_bf16_f32 v43, v108, v109
	v_addc_co_u32_e32 v45, vcc, 0, v45, vcc
	v_pk_mul_f32 v[32:33], v[4:5], v[32:33]
	global_store_dwordx4 v[44:45], v[40:43], off
	v_pk_mul_f32 v[36:37], v[36:37], v[96:97] op_sel_hi:[1,0]
	v_pk_mul_f32 v[38:39], v[38:39], v[96:97] op_sel_hi:[1,0]
	v_pk_fma_f32 v[40:41], v[140:141], v[32:33], v[100:101]
	v_pk_mul_f32 v[32:33], v[34:35], v[96:97] op_sel_hi:[1,0]
	v_pk_mul_f32 v[36:37], v[0:1], v[36:37]
	v_pk_mul_f32 v[38:39], v[2:3], v[38:39]
	v_pk_mul_f32 v[32:33], v[6:7], v[32:33]
	v_pk_fma_f32 v[36:37], v[130:131], v[36:37], v[104:105]
	v_pk_fma_f32 v[38:39], v[142:143], v[38:39], v[106:107]
	v_pk_fma_f32 v[42:43], v[144:145], v[32:33], v[102:103]
	v_cvt_pk_bf16_f32 v32, v36, v37
	v_cvt_pk_bf16_f32 v33, v38, v39
	v_cvt_pk_bf16_f32 v34, v40, v41
	v_cvt_pk_bf16_f32 v35, v42, v43
	global_store_dwordx4 v[44:45], v[32:35], off offset:1024
	s_waitcnt vmcnt(6)
	v_mov_b64_e32 v[36:37], v[76:77]
	v_mov_b64_e32 v[40:41], v[56:57]
	v_mov_b64_e32 v[32:33], v[72:73]
	v_mov_b64_e32 v[44:45], v[60:61]
	v_mov_b64_e32 v[98:99], v[82:83]
	v_mov_b64_e32 v[110:111], v[86:87]
	v_lshl_add_u64 v[114:115], v[114:115], 0, s[24:25]
	v_mov_b64_e32 v[34:35], v[74:75]
	v_mov_b64_e32 v[38:39], v[78:79]
	v_mov_b64_e32 v[42:43], v[58:59]
	v_mov_b64_e32 v[46:47], v[62:63]
	v_mov_b64_e32 v[96:97], v[80:81]
	v_mov_b64_e32 v[108:109], v[84:85]
	s_andn2_b64 exec, exec, s[18:19]
	s_cbranch_execz .LBB0_832

.LBB0_830:
	s_or_b64 exec, exec, s[28:29]
	v_ashrrev_i32_e32 v156, 13, v153
	v_cmp_ne_u32_e32 vcc, v156, v129
	s_and_saveexec_b64 s[28:29], vcc
	s_cbranch_execz .LBB0_827
	v_mul_hi_i32_i24_e32 v65, 0x3000, v156
	v_mul_i32_i24_e32 v64, 0x3000, v156
	v_lshl_add_u64 v[48:49], s[8:9], 0, v[64:65]
	v_lshl_add_u64 v[90:91], v[116:117], 0, v[64:65]
	v_lshl_add_u64 v[88:89], v[48:49], 0, s[20:21]
	v_add_co_u32_e32 v94, vcc, s34, v90
	v_lshl_add_u64 v[52:53], v[88:89], 0, v[112:113]
	s_nop 0
	v_addc_co_u32_e32 v95, vcc, 0, v91, vcc
	global_load_dwordx4 v[48:51], v[52:53], off
	s_nop 0
	global_load_dwordx4 v[52:55], v[52:53], off offset:16
	s_nop 0
	global_load_dwordx4 v[64:67], v[90:91], off
	global_load_dwordx4 v[68:71], v[90:91], off offset:16
	v_lshl_add_u64 v[92:93], v[90:91], 0, s[16:17]
	global_load_dwordx4 v[130:133], v[94:95], off
	global_load_dwordx4 v[140:143], v[92:93], off offset:16
	v_mov_b32_e32 v129, v113
	v_lshl_add_u64 v[88:89], v[88:89], 0, v[128:129]
	v_lshl_add_u64 v[92:93], v[90:91], 0, s[22:23]
	global_load_dwordx4 v[158:161], v[94:95], off offset:2048
	global_load_dwordx4 v[162:165], v[92:93], off offset:16
	global_load_dwordx4 v[104:107], v[90:91], off offset:2048
	global_load_dwordx4 v[100:103], v[90:91], off offset:2064
	s_nop 0
	global_load_dwordx4 v[92:95], v[88:89], off
	s_nop 0
	global_load_dwordx4 v[88:91], v[88:89], off offset:16
	v_mov_b32_e32 v129, v156
	s_waitcnt vmcnt(7)
	v_pk_add_f32 v[138:139], v[130:131], 1.0 op_sel_hi:[1,0]
	v_pk_add_f32 v[136:137], v[132:133], 1.0 op_sel_hi:[1,0]
	s_waitcnt vmcnt(6)
	v_pk_add_f32 v[134:135], v[140:141], 1.0 op_sel_hi:[1,0]
	v_pk_add_f32 v[132:133], v[142:143], 1.0 op_sel_hi:[1,0]
	s_waitcnt vmcnt(5)
	v_pk_add_f32 v[130:131], v[158:159], 1.0 op_sel_hi:[1,0]
	v_pk_add_f32 v[142:143], v[160:161], 1.0 op_sel_hi:[1,0]
	s_waitcnt vmcnt(0)
	v_pk_add_f32 v[140:141], v[162:163], 1.0 op_sel_hi:[1,0]
	v_pk_add_f32 v[144:145], v[164:165], 1.0 op_sel_hi:[1,0]
	s_branch .LBB0_827

.LBB0_866:
	s_or_b64 exec, exec, s[20:21]
	v_lshlrev_b32_e32 v158, 16, v108
	v_and_b32_e32 v159, 0xffff0000, v108
	v_lshlrev_b32_e32 v108, 16, v109
	v_and_b32_e32 v109, 0xffff0000, v109
	v_pk_mul_f32 v[166:167], v[158:159], v[158:159]
	v_pk_mul_f32 v[168:169], v[108:109], v[108:109]
	v_add_f32_e32 v157, v166, v167
	v_lshlrev_b32_e32 v160, 16, v110
	v_and_b32_e32 v161, 0xffff0000, v110
	v_add_f32_e32 v157, v168, v157
	v_pk_mul_f32 v[170:171], v[160:161], v[160:161]
	v_add_f32_e32 v157, v169, v157
	v_lshlrev_b32_e32 v110, 16, v111
	v_and_b32_e32 v111, 0xffff0000, v111
	v_add_f32_e32 v157, v170, v157
	v_pk_mul_f32 v[172:173], v[110:111], v[110:111]
	v_add_f32_e32 v157, v171, v157
	v_lshlrev_b32_e32 v162, 16, v100
	v_and_b32_e32 v163, 0xffff0000, v100
	v_add_f32_e32 v157, v172, v157
	v_pk_mul_f32 v[174:175], v[162:163], v[162:163]
	v_add_f32_e32 v157, v173, v157
	v_lshlrev_b32_e32 v100, 16, v101
	v_and_b32_e32 v101, 0xffff0000, v101
	v_add_f32_e32 v157, v174, v157
	v_pk_mul_f32 v[176:177], v[100:101], v[100:101]
	v_add_f32_e32 v157, v175, v157
	v_lshlrev_b32_e32 v164, 16, v102
	v_and_b32_e32 v165, 0xffff0000, v102
	v_add_f32_e32 v157, v176, v157
	v_pk_mul_f32 v[178:179], v[164:165], v[164:165]
	v_add_f32_e32 v157, v177, v157
	v_lshlrev_b32_e32 v102, 16, v103
	v_and_b32_e32 v103, 0xffff0000, v103
	v_add_f32_e32 v157, v178, v157
	v_pk_mul_f32 v[180:181], v[102:103], v[102:103]
	v_add_f32_e32 v157, v179, v157
	v_add_f32_e32 v157, v180, v157
	v_add_f32_e32 v157, v181, v157
	ds_bpermute_b32 v166, v113, v157
	v_lshl_add_u64 v[128:129], v[128:129], 0, s[16:17]
	s_waitcnt lgkmcnt(0)
	v_add_f32_e32 v157, v157, v166
	ds_bpermute_b32 v166, v150, v157
	s_waitcnt lgkmcnt(0)
	v_add_f32_e32 v157, v157, v166
	ds_bpermute_b32 v166, v151, v157
	s_waitcnt lgkmcnt(0)
	v_add_f32_e32 v157, v157, v166
	ds_bpermute_b32 v166, v152, v157
	s_waitcnt lgkmcnt(0)
	v_add_f32_e32 v157, v157, v166
	ds_bpermute_b32 v166, v153, v157
	s_waitcnt lgkmcnt(0)
	v_add_f32_e32 v157, v157, v166
	ds_bpermute_b32 v166, v155, v157
	s_waitcnt lgkmcnt(0)
	v_add_f32_e32 v157, v157, v166
	v_fmamk_f32 v157, v157, 0x3a800000, v156
	v_mul_f32_e32 v166, 0x4b800000, v157
	v_cmp_gt_f32_e32 vcc, s30, v157
	s_nop 1
	v_cndmask_b32_e32 v157, v157, v166, vcc
	v_rsq_f32_e32 v157, v157
	s_nop 0
	v_mul_f32_e32 v166, 0x45800000, v157
	v_cndmask_b32_e32 v166, v157, v166, vcc
	v_pk_mul_f32 v[100:101], v[166:167], v[100:101] op_sel_hi:[0,1]
	v_pk_mul_f32 v[100:101], v[18:19], v[100:101]
	v_pk_mul_f32 v[108:109], v[166:167], v[108:109] op_sel_hi:[0,1]
	s_nop 0
	v_pk_fma_f32 v[46:47], v[78:79], v[100:101], v[46:47]
	v_pk_mul_f32 v[100:101], v[166:167], v[164:165] op_sel_hi:[0,1]
	v_pk_mul_f32 v[158:159], v[166:167], v[158:159] op_sel_hi:[0,1]
	v_pk_mul_f32 v[160:161], v[166:167], v[160:161] op_sel_hi:[0,1]
	v_pk_mul_f32 v[108:109], v[2:3], v[108:109]
	v_pk_mul_f32 v[100:101], v[20:21], v[100:101]
	v_pk_mul_f32 v[158:159], v[0:1], v[158:159]
	v_pk_fma_f32 v[62:63], v[38:39], v[108:109], v[62:63]
	v_pk_mul_f32 v[108:109], v[4:5], v[160:161]
	s_nop 0
	v_pk_fma_f32 v[32:33], v[72:73], v[100:101], v[32:33]
	v_pk_mul_f32 v[100:101], v[166:167], v[102:103] op_sel_hi:[0,1]
	v_pk_fma_f32 v[60:61], v[36:37], v[158:159], v[60:61]
	v_pk_fma_f32 v[48:49], v[40:41], v[108:109], v[48:49]
	v_pk_mul_f32 v[108:109], v[166:167], v[110:111] op_sel_hi:[0,1]
	v_pk_mul_f32 v[100:101], v[22:23], v[100:101]
	v_pk_mul_f32 v[108:109], v[6:7], v[108:109]
	v_pk_fma_f32 v[34:35], v[74:75], v[100:101], v[34:35]
	v_pk_mul_f32 v[100:101], v[60:61], v[60:61]
	v_pk_fma_f32 v[50:51], v[42:43], v[108:109], v[50:51]
	v_pk_mul_f32 v[108:109], v[166:167], v[162:163] op_sel_hi:[0,1]
	v_pk_mul_f32 v[102:103], v[62:63], v[62:63]
	v_add_f32_e32 v100, v100, v101
	v_pk_mul_f32 v[108:109], v[16:17], v[108:109]
	v_add_f32_e32 v100, v102, v100
	v_pk_fma_f32 v[44:45], v[76:77], v[108:109], v[44:45]
	v_pk_mul_f32 v[108:109], v[48:49], v[48:49]
	v_add_f32_e32 v100, v103, v100
	v_add_f32_e32 v100, v108, v100
	v_pk_mul_f32 v[110:111], v[50:51], v[50:51]
	v_add_f32_e32 v100, v109, v100
	v_add_f32_e32 v100, v110, v100
	v_pk_mul_f32 v[158:159], v[44:45], v[44:45]
	v_add_f32_e32 v100, v111, v100
	v_add_f32_e32 v100, v158, v100
	v_pk_mul_f32 v[160:161], v[46:47], v[46:47]
	v_add_f32_e32 v100, v159, v100
	v_add_f32_e32 v100, v160, v100
	v_pk_mul_f32 v[162:163], v[32:33], v[32:33]
	v_add_f32_e32 v100, v161, v100
	v_add_f32_e32 v100, v162, v100
	v_pk_mul_f32 v[164:165], v[34:35], v[34:35]
	v_add_f32_e32 v100, v163, v100
	v_add_f32_e32 v100, v164, v100
	v_add_f32_e32 v100, v165, v100
	ds_bpermute_b32 v101, v113, v100
	v_cmp_gt_i32_e32 vcc, s24, v149
	v_mov_b32_e32 v110, s26
	v_mov_b32_e32 v111, s7
	s_waitcnt lgkmcnt(0)
	v_add_f32_e32 v100, v100, v101
	ds_bpermute_b32 v101, v150, v100
	s_waitcnt lgkmcnt(0)
	v_add_f32_e32 v108, v100, v101
	ds_bpermute_b32 v109, v151, v108
	v_lshl_add_u64 v[100:101], v[118:119], 0, s[18:19]
	v_cndmask_b32_e32 v102, v149, v100, vcc
	v_cndmask_b32_e32 v100, v148, v100, vcc
	v_cndmask_b32_e32 v103, 0, v101, vcc
	s_waitcnt lgkmcnt(0)
	v_add_f32_e32 v108, v108, v109
	ds_bpermute_b32 v109, v152, v108
	v_mov_b32_e32 v101, v103
	v_lshlrev_b64 v[100:101], 12, v[100:101]
	v_lshlrev_b64 v[102:103], 11, v[102:103]
	s_add_u32 s18, s18, 0x80
	s_waitcnt lgkmcnt(0)
	v_add_f32_e32 v148, v108, v109
	ds_bpermute_b32 v149, v153, v148
	v_cndmask_b32_e32 v109, v110, v111, vcc
	v_mov_b32_e32 v108, s25
	v_mov_b32_e32 v110, s6
	v_cndmask_b32_e32 v108, v108, v110, vcc
	s_waitcnt lgkmcnt(0)
	v_add_f32_e32 v110, v148, v149
	ds_bpermute_b32 v111, v155, v110
	v_lshl_add_u64 v[100:101], v[108:109], 0, v[100:101]
	v_lshl_add_u64 v[100:101], v[100:101], 0, v[114:115]
	global_store_dwordx4 v[100:101], v[60:63], off
	global_store_dwordx4 v[100:101], v[48:51], off offset:16
	global_store_dwordx4 v[100:101], v[44:47], off offset:2048
	global_store_dwordx4 v[100:101], v[32:35], off offset:2064
	s_waitcnt lgkmcnt(0)
	v_add_f32_e32 v108, v110, v111
	v_fmamk_f32 v108, v108, 0x3a800000, v156
	v_mul_f32_e32 v109, 0x4b800000, v108
	v_cmp_gt_f32_e32 vcc, s30, v108
	s_addc_u32 s19, s19, 0
	s_nop 0
	v_cndmask_b32_e32 v108, v108, v109, vcc
	v_rsq_f32_e32 v108, v108
	s_nop 0
	v_mul_f32_e32 v100, 0x45800000, v108
	v_cndmask_b32_e32 v100, v108, v100, vcc
	v_pk_mul_f32 v[48:49], v[48:49], v[100:101] op_sel_hi:[1,0]
	v_pk_mul_f32 v[60:61], v[60:61], v[100:101] op_sel_hi:[1,0]
	v_pk_mul_f32 v[48:49], v[12:13], v[48:49]
	v_pk_mul_f32 v[62:63], v[62:63], v[100:101] op_sel_hi:[1,0]
	v_pk_fma_f32 v[108:109], v[136:137], v[48:49], v[56:57]
	v_pk_mul_f32 v[48:49], v[50:51], v[100:101] op_sel_hi:[1,0]
	v_pk_mul_f32 v[60:61], v[8:9], v[60:61]
	v_pk_mul_f32 v[62:63], v[10:11], v[62:63]
	v_pk_mul_f32 v[48:49], v[14:15], v[48:49]
	v_pk_fma_f32 v[60:61], v[140:141], v[60:61], v[52:53]
	v_pk_fma_f32 v[62:63], v[138:139], v[62:63], v[54:55]
	v_pk_fma_f32 v[110:111], v[134:135], v[48:49], v[58:59]
	v_pk_mul_f32 v[32:33], v[32:33], v[100:101] op_sel_hi:[1,0]
	v_cvt_pk_bf16_f32 v48, v60, v61
	v_cvt_pk_bf16_f32 v49, v62, v63
	v_cvt_pk_bf16_f32 v50, v108, v109
	v_cvt_pk_bf16_f32 v51, v110, v111
	v_lshl_add_u64 v[60:61], v[124:125], 0, v[102:103]
	v_pk_mul_f32 v[32:33], v[28:29], v[32:33]
	global_store_dwordx4 v[60:61], v[48:51], off
	v_pk_mul_f32 v[44:45], v[44:45], v[100:101] op_sel_hi:[1,0]
	v_pk_mul_f32 v[46:47], v[46:47], v[100:101] op_sel_hi:[1,0]
	v_pk_fma_f32 v[48:49], v[142:143], v[32:33], v[88:89]
	v_pk_mul_f32 v[32:33], v[34:35], v[100:101] op_sel_hi:[1,0]
	v_pk_mul_f32 v[44:45], v[24:25], v[44:45]
	v_pk_mul_f32 v[46:47], v[26:27], v[46:47]
	v_pk_mul_f32 v[32:33], v[30:31], v[32:33]
	v_pk_fma_f32 v[44:45], v[132:133], v[44:45], v[92:93]
	v_pk_fma_f32 v[46:47], v[144:145], v[46:47], v[94:95]
	v_pk_fma_f32 v[50:51], v[146:147], v[32:33], v[90:91]
	v_cvt_pk_bf16_f32 v32, v44, v45
	v_cvt_pk_bf16_f32 v33, v46, v47
	v_cvt_pk_bf16_f32 v34, v48, v49
	v_cvt_pk_bf16_f32 v35, v50, v51
	global_store_dwordx4 v[60:61], v[32:35], off offset:1024
	s_waitcnt vmcnt(6)
	v_mov_b64_e32 v[44:45], v[80:81]
	v_mov_b64_e32 v[48:49], v[68:69]
	v_add_u32_e32 v32, s18, v116
	v_add_u32_e32 v32, 0x7f80, v32
	v_cmp_lt_i32_e32 vcc, s31, v32
	v_mov_b64_e32 v[32:33], v[84:85]
	v_mov_b64_e32 v[60:61], v[64:65]
	v_mov_b64_e32 v[100:101], v[104:105]
	v_mov_b64_e32 v[110:111], v[98:99]
	s_or_b64 s[10:11], vcc, s[10:11]
	v_mov_b64_e32 v[34:35], v[86:87]
	v_mov_b64_e32 v[46:47], v[82:83]
	v_mov_b64_e32 v[50:51], v[70:71]
	v_mov_b64_e32 v[62:63], v[66:67]
	v_mov_b64_e32 v[102:103], v[106:107]
	v_mov_b64_e32 v[108:109], v[96:97]
	s_andn2_b64 exec, exec, s[10:11]
	s_cbranch_execz .LBB0_875

.LBB0_873:
	s_or_b64 exec, exec, s[20:21]
	v_min_i32_e32 v114, 0x8000, v149
	v_ashrrev_i32_e32 v157, 13, v114
	v_cmp_ne_u32_e32 vcc, v157, v131
	v_lshlrev_b32_e32 v114, 2, v112
	s_and_saveexec_b64 s[20:21], vcc
	s_cbranch_execz .LBB0_866
	v_mul_hi_i32_i24_e32 v53, 0x3000, v157
	v_mul_i32_i24_e32 v52, 0x3000, v157
	v_lshl_add_u64 v[36:37], s[8:9], 0, v[52:53]
	v_lshl_add_u64 v[74:75], v[122:123], 0, v[52:53]
	v_lshl_add_u64 v[72:73], v[36:37], 0, s[12:13]
	v_add_co_u32_e32 v78, vcc, s29, v74
	v_lshl_add_u64 v[54:55], v[72:73], 0, v[114:115]
	s_nop 0
	v_addc_co_u32_e32 v79, vcc, 0, v75, vcc
	global_load_dwordx4 v[36:39], v[54:55], off
	global_load_dwordx4 v[40:43], v[54:55], off offset:16
	s_nop 0
	global_load_dwordx4 v[52:55], v[74:75], off
	global_load_dwordx4 v[56:59], v[74:75], off offset:16
	v_lshl_add_u64 v[76:77], v[74:75], 0, s[2:3]
	global_load_dwordx4 v[132:135], v[78:79], off
	global_load_dwordx4 v[142:145], v[76:77], off offset:16
	v_mov_b32_e32 v131, v115
	v_lshl_add_u64 v[72:73], v[72:73], 0, v[130:131]
	v_lshl_add_u64 v[76:77], v[74:75], 0, s[14:15]
	global_load_dwordx4 v[158:161], v[78:79], off offset:2048
	global_load_dwordx4 v[162:165], v[76:77], off offset:16
	global_load_dwordx4 v[92:95], v[74:75], off offset:2048
	global_load_dwordx4 v[88:91], v[74:75], off offset:2064
	s_nop 0
	global_load_dwordx4 v[76:79], v[72:73], off
	s_nop 0
	global_load_dwordx4 v[72:75], v[72:73], off offset:16
	v_mov_b32_e32 v131, v157
	s_waitcnt vmcnt(7)
	v_pk_add_f32 v[140:141], v[132:133], 1.0 op_sel_hi:[1,0]
	v_pk_add_f32 v[138:139], v[134:135], 1.0 op_sel_hi:[1,0]
	s_waitcnt vmcnt(6)
	v_pk_add_f32 v[136:137], v[142:143], 1.0 op_sel_hi:[1,0]
	v_pk_add_f32 v[134:135], v[144:145], 1.0 op_sel_hi:[1,0]
	s_waitcnt vmcnt(5)
	v_pk_add_f32 v[132:133], v[158:159], 1.0 op_sel_hi:[1,0]
	v_pk_add_f32 v[144:145], v[160:161], 1.0 op_sel_hi:[1,0]
	s_waitcnt vmcnt(0)
	v_pk_add_f32 v[142:143], v[162:163], 1.0 op_sel_hi:[1,0]
	v_pk_add_f32 v[146:147], v[164:165], 1.0 op_sel_hi:[1,0]
	s_branch .LBB0_866

.LBB0_1320:
	s_or_b64 exec, exec, s[22:23]
	v_lshlrev_b32_e32 v156, 16, v108
	v_and_b32_e32 v157, 0xffff0000, v108
	v_lshlrev_b32_e32 v108, 16, v109
	v_and_b32_e32 v109, 0xffff0000, v109
	v_pk_mul_f32 v[164:165], v[156:157], v[156:157]
	v_pk_mul_f32 v[166:167], v[108:109], v[108:109]
	v_add_f32_e32 v164, v164, v165
	v_lshlrev_b32_e32 v158, 16, v110
	v_and_b32_e32 v159, 0xffff0000, v110
	v_add_f32_e32 v164, v166, v164
	v_pk_mul_f32 v[168:169], v[158:159], v[158:159]
	v_add_f32_e32 v164, v167, v164
	v_lshlrev_b32_e32 v110, 16, v111
	v_and_b32_e32 v111, 0xffff0000, v111
	v_add_f32_e32 v164, v168, v164
	v_pk_mul_f32 v[170:171], v[110:111], v[110:111]
	v_add_f32_e32 v164, v169, v164
	v_lshlrev_b32_e32 v160, 16, v96
	v_and_b32_e32 v161, 0xffff0000, v96
	v_add_f32_e32 v164, v170, v164
	v_pk_mul_f32 v[172:173], v[160:161], v[160:161]
	v_add_f32_e32 v164, v171, v164
	v_lshlrev_b32_e32 v96, 16, v97
	v_and_b32_e32 v97, 0xffff0000, v97
	v_add_f32_e32 v164, v172, v164
	v_pk_mul_f32 v[174:175], v[96:97], v[96:97]
	v_add_f32_e32 v164, v173, v164
	v_lshlrev_b32_e32 v162, 16, v98
	v_and_b32_e32 v163, 0xffff0000, v98
	v_add_f32_e32 v164, v174, v164
	v_pk_mul_f32 v[176:177], v[162:163], v[162:163]
	v_add_f32_e32 v164, v175, v164
	v_lshlrev_b32_e32 v98, 16, v99
	v_and_b32_e32 v99, 0xffff0000, v99
	v_add_f32_e32 v164, v176, v164
	v_pk_mul_f32 v[178:179], v[98:99], v[98:99]
	v_add_f32_e32 v164, v177, v164
	v_add_f32_e32 v164, v178, v164
	v_add_f32_e32 v164, v179, v164
	ds_bpermute_b32 v165, v147, v164
	s_and_b64 s[2:3], exec, s[2:3]
	s_or_b64 s[12:13], s[2:3], s[12:13]
	v_lshl_add_u64 v[124:125], v[124:125], 0, s[20:21]
	v_lshl_add_u64 v[126:127], v[126:127], 0, s[18:19]
	s_waitcnt lgkmcnt(0)
	v_add_f32_e32 v164, v164, v165
	ds_bpermute_b32 v165, v148, v164
	s_waitcnt lgkmcnt(0)
	v_add_f32_e32 v164, v164, v165
	ds_bpermute_b32 v165, v149, v164
	s_waitcnt lgkmcnt(0)
	v_add_f32_e32 v164, v164, v165
	ds_bpermute_b32 v165, v150, v164
	s_waitcnt lgkmcnt(0)
	v_add_f32_e32 v164, v164, v165
	ds_bpermute_b32 v165, v151, v164
	s_waitcnt lgkmcnt(0)
	v_add_f32_e32 v164, v164, v165
	ds_bpermute_b32 v165, v152, v164
	s_waitcnt lgkmcnt(0)
	v_add_f32_e32 v164, v164, v165
	v_fmamk_f32 v164, v164, 0x3a800000, v155
	v_mul_f32_e32 v165, 0x4b800000, v164
	v_cmp_gt_f32_e32 vcc, s27, v164
	s_nop 1
	v_cndmask_b32_e32 v164, v164, v165, vcc
	v_rsq_f32_e32 v164, v164
	s_nop 0
	v_mul_f32_e32 v165, 0x45800000, v164
	v_cndmask_b32_e32 v164, v164, v165, vcc
	v_pk_mul_f32 v[96:97], v[164:165], v[96:97] op_sel_hi:[0,1]
	v_pk_mul_f32 v[96:97], v[10:11], v[96:97]
	v_pk_mul_f32 v[108:109], v[164:165], v[108:109] op_sel_hi:[0,1]
	s_nop 0
	v_pk_fma_f32 v[38:39], v[94:95], v[96:97], v[38:39]
	v_pk_mul_f32 v[96:97], v[164:165], v[162:163] op_sel_hi:[0,1]
	v_pk_mul_f32 v[156:157], v[164:165], v[156:157] op_sel_hi:[0,1]
	v_pk_mul_f32 v[158:159], v[164:165], v[158:159] op_sel_hi:[0,1]
	v_pk_mul_f32 v[108:109], v[26:27], v[108:109]
	v_pk_mul_f32 v[96:97], v[12:13], v[96:97]
	v_pk_mul_f32 v[156:157], v[24:25], v[156:157]
	v_pk_fma_f32 v[46:47], v[50:51], v[108:109], v[46:47]
	v_pk_mul_f32 v[108:109], v[28:29], v[158:159]
	s_nop 0
	v_pk_fma_f32 v[32:33], v[88:89], v[96:97], v[32:33]
	v_pk_mul_f32 v[96:97], v[164:165], v[98:99] op_sel_hi:[0,1]
	v_pk_fma_f32 v[44:45], v[48:49], v[156:157], v[44:45]
	v_pk_fma_f32 v[40:41], v[52:53], v[108:109], v[40:41]
	v_pk_mul_f32 v[108:109], v[164:165], v[110:111] op_sel_hi:[0,1]
	v_pk_mul_f32 v[96:97], v[14:15], v[96:97]
	v_pk_mul_f32 v[108:109], v[30:31], v[108:109]
	v_pk_fma_f32 v[34:35], v[90:91], v[96:97], v[34:35]
	v_pk_mul_f32 v[96:97], v[44:45], v[44:45]
	v_pk_fma_f32 v[42:43], v[54:55], v[108:109], v[42:43]
	v_pk_mul_f32 v[108:109], v[164:165], v[160:161] op_sel_hi:[0,1]
	v_pk_mul_f32 v[98:99], v[46:47], v[46:47]
	v_add_f32_e32 v96, v96, v97
	v_pk_mul_f32 v[108:109], v[8:9], v[108:109]
	v_add_f32_e32 v96, v98, v96
	v_pk_fma_f32 v[36:37], v[92:93], v[108:109], v[36:37]
	v_pk_mul_f32 v[108:109], v[40:41], v[40:41]
	v_add_f32_e32 v96, v99, v96
	v_add_f32_e32 v96, v108, v96
	v_pk_mul_f32 v[110:111], v[42:43], v[42:43]
	v_add_f32_e32 v96, v109, v96
	v_add_f32_e32 v96, v110, v96
	v_pk_mul_f32 v[156:157], v[36:37], v[36:37]
	v_add_f32_e32 v96, v111, v96
	v_add_f32_e32 v96, v156, v96
	v_pk_mul_f32 v[158:159], v[38:39], v[38:39]
	v_add_f32_e32 v96, v157, v96
	v_add_f32_e32 v96, v158, v96
	v_pk_mul_f32 v[160:161], v[32:33], v[32:33]
	v_add_f32_e32 v96, v159, v96
	v_add_f32_e32 v96, v160, v96
	v_pk_mul_f32 v[162:163], v[34:35], v[34:35]
	v_add_f32_e32 v96, v161, v96
	v_add_f32_e32 v96, v162, v96
	v_add_f32_e32 v96, v163, v96
	ds_bpermute_b32 v97, v147, v96
	s_waitcnt lgkmcnt(0)
	v_add_f32_e32 v96, v96, v97
	ds_bpermute_b32 v97, v148, v96
	s_waitcnt lgkmcnt(0)
	v_add_f32_e32 v96, v96, v97
	ds_bpermute_b32 v97, v149, v96
	s_waitcnt lgkmcnt(0)
	v_add_f32_e32 v96, v96, v97
	ds_bpermute_b32 v97, v150, v96
	s_waitcnt lgkmcnt(0)
	v_add_f32_e32 v96, v96, v97
	ds_bpermute_b32 v97, v151, v96
	s_waitcnt lgkmcnt(0)
	v_add_f32_e32 v98, v96, v97
	ds_bpermute_b32 v99, v152, v98
	v_lshl_add_u64 v[96:97], v[114:115], 0, v[122:123]
	global_store_dwordx4 v[96:97], v[44:47], off
	global_store_dwordx4 v[96:97], v[40:43], off offset:16
	global_store_dwordx4 v[96:97], v[36:39], off offset:2048
	global_store_dwordx4 v[96:97], v[32:35], off offset:2064
	v_lshl_add_u64 v[114:115], v[114:115], 0, s[20:21]
	s_waitcnt lgkmcnt(0)
	v_add_f32_e32 v98, v98, v99
	v_fmamk_f32 v98, v98, 0x3a800000, v155
	v_mul_f32_e32 v99, 0x4b800000, v98
	v_cmp_gt_f32_e32 vcc, s27, v98
	s_nop 1
	v_cndmask_b32_e32 v98, v98, v99, vcc
	v_rsq_f32_e32 v98, v98
	s_nop 0
	v_mul_f32_e32 v96, 0x45800000, v98
	v_cndmask_b32_e32 v96, v98, v96, vcc
	v_pk_mul_f32 v[40:41], v[40:41], v[96:97] op_sel_hi:[1,0]
	v_pk_mul_f32 v[44:45], v[44:45], v[96:97] op_sel_hi:[1,0]
	v_pk_mul_f32 v[40:41], v[20:21], v[40:41]
	v_pk_mul_f32 v[44:45], v[16:17], v[44:45]
	v_pk_fma_f32 v[98:99], v[134:135], v[40:41], v[68:69]
	v_pk_mul_f32 v[40:41], v[42:43], v[96:97] op_sel_hi:[1,0]
	v_pk_fma_f32 v[44:45], v[138:139], v[44:45], v[64:65]
	v_pk_mul_f32 v[46:47], v[46:47], v[96:97] op_sel_hi:[1,0]
	v_pk_mul_f32 v[40:41], v[22:23], v[40:41]
	v_pk_mul_f32 v[46:47], v[18:19], v[46:47]
	v_pk_fma_f32 v[108:109], v[132:133], v[40:41], v[70:71]
	v_cvt_pk_bf16_f32 v40, v44, v45
	v_lshl_add_u64 v[44:45], v[116:117], 0, v[120:121]
	v_pk_fma_f32 v[46:47], v[136:137], v[46:47], v[66:67]
	v_add_co_u32_e32 v44, vcc, s28, v44
	v_pk_mul_f32 v[32:33], v[32:33], v[96:97] op_sel_hi:[1,0]
	v_cvt_pk_bf16_f32 v41, v46, v47
	v_cvt_pk_bf16_f32 v42, v98, v99
	v_cvt_pk_bf16_f32 v43, v108, v109
	v_addc_co_u32_e32 v45, vcc, 0, v45, vcc
	v_pk_mul_f32 v[32:33], v[4:5], v[32:33]
	global_store_dwordx4 v[44:45], v[40:43], off
	v_pk_mul_f32 v[36:37], v[36:37], v[96:97] op_sel_hi:[1,0]
	v_pk_mul_f32 v[38:39], v[38:39], v[96:97] op_sel_hi:[1,0]
	v_pk_fma_f32 v[40:41], v[140:141], v[32:33], v[100:101]
	v_pk_mul_f32 v[32:33], v[34:35], v[96:97] op_sel_hi:[1,0]
	v_pk_mul_f32 v[36:37], v[0:1], v[36:37]
	v_pk_mul_f32 v[38:39], v[2:3], v[38:39]
	v_pk_mul_f32 v[32:33], v[6:7], v[32:33]
	v_pk_fma_f32 v[36:37], v[130:131], v[36:37], v[104:105]
	v_pk_fma_f32 v[38:39], v[142:143], v[38:39], v[106:107]
	v_pk_fma_f32 v[42:43], v[144:145], v[32:33], v[102:103]
	v_cvt_pk_bf16_f32 v32, v36, v37
	v_cvt_pk_bf16_f32 v33, v38, v39
	v_cvt_pk_bf16_f32 v34, v40, v41
	v_cvt_pk_bf16_f32 v35, v42, v43
	global_store_dwordx4 v[44:45], v[32:35], off offset:1024
	s_waitcnt vmcnt(6)
	v_mov_b64_e32 v[36:37], v[76:77]
	v_mov_b64_e32 v[40:41], v[56:57]
	v_mov_b64_e32 v[32:33], v[72:73]
	v_mov_b64_e32 v[44:45], v[60:61]
	v_mov_b64_e32 v[98:99], v[82:83]
	v_mov_b64_e32 v[110:111], v[86:87]
	v_lshl_add_u64 v[116:117], v[116:117], 0, s[18:19]
	v_mov_b64_e32 v[34:35], v[74:75]
	v_mov_b64_e32 v[38:39], v[78:79]
	v_mov_b64_e32 v[42:43], v[58:59]
	v_mov_b64_e32 v[46:47], v[62:63]
	v_mov_b64_e32 v[96:97], v[80:81]
	v_mov_b64_e32 v[108:109], v[84:85]
	s_andn2_b64 exec, exec, s[12:13]
	s_cbranch_execz .LBB0_1325

.LBB0_1323:
	s_or_b64 exec, exec, s[22:23]
	v_ashrrev_i32_e32 v156, 13, v153
	v_cmp_ne_u32_e32 vcc, v156, v129
	s_and_saveexec_b64 s[22:23], vcc
	s_cbranch_execz .LBB0_1320
	v_mul_hi_i32_i24_e32 v65, 0x3000, v156
	v_mul_i32_i24_e32 v64, 0x3000, v156
	v_lshl_add_u64 v[48:49], s[6:7], 0, v[64:65]
	v_lshl_add_u64 v[90:91], v[118:119], 0, v[64:65]
	v_lshl_add_u64 v[88:89], v[48:49], 0, s[14:15]
	v_add_co_u32_e32 v94, vcc, s26, v90
	v_lshl_add_u64 v[66:67], v[88:89], 0, v[112:113]
	s_nop 0
	v_addc_co_u32_e32 v95, vcc, 0, v91, vcc
	global_load_dwordx4 v[48:51], v[66:67], off
	global_load_dwordx4 v[52:55], v[66:67], off offset:16
	s_nop 0
	global_load_dwordx4 v[64:67], v[90:91], off
	global_load_dwordx4 v[68:71], v[90:91], off offset:16
	v_lshl_add_u64 v[92:93], v[90:91], 0, s[10:11]
	global_load_dwordx4 v[130:133], v[94:95], off
	global_load_dwordx4 v[140:143], v[92:93], off offset:16
	v_mov_b32_e32 v129, v113
	v_lshl_add_u64 v[88:89], v[88:89], 0, v[128:129]
	v_lshl_add_u64 v[92:93], v[90:91], 0, s[16:17]
	global_load_dwordx4 v[158:161], v[94:95], off offset:2048
	global_load_dwordx4 v[162:165], v[92:93], off offset:16
	global_load_dwordx4 v[104:107], v[90:91], off offset:2048
	global_load_dwordx4 v[100:103], v[90:91], off offset:2064
	s_nop 0
	global_load_dwordx4 v[92:95], v[88:89], off
	s_nop 0
	global_load_dwordx4 v[88:91], v[88:89], off offset:16
	v_mov_b32_e32 v129, v156
	s_waitcnt vmcnt(7)
	v_pk_add_f32 v[138:139], v[130:131], 1.0 op_sel_hi:[1,0]
	v_pk_add_f32 v[136:137], v[132:133], 1.0 op_sel_hi:[1,0]
	s_waitcnt vmcnt(6)
	v_pk_add_f32 v[134:135], v[140:141], 1.0 op_sel_hi:[1,0]
	v_pk_add_f32 v[132:133], v[142:143], 1.0 op_sel_hi:[1,0]
	s_waitcnt vmcnt(5)
	v_pk_add_f32 v[130:131], v[158:159], 1.0 op_sel_hi:[1,0]
	v_pk_add_f32 v[142:143], v[160:161], 1.0 op_sel_hi:[1,0]
	s_waitcnt vmcnt(0)
	v_pk_add_f32 v[140:141], v[162:163], 1.0 op_sel_hi:[1,0]
	v_pk_add_f32 v[144:145], v[164:165], 1.0 op_sel_hi:[1,0]
	s_branch .LBB0_1320

.LBB0_1359:
	s_or_b64 exec, exec, s[20:21]
	v_lshlrev_b32_e32 v158, 16, v108
	v_and_b32_e32 v159, 0xffff0000, v108
	v_lshlrev_b32_e32 v108, 16, v109
	v_and_b32_e32 v109, 0xffff0000, v109
	v_pk_mul_f32 v[166:167], v[158:159], v[158:159]
	v_pk_mul_f32 v[168:169], v[108:109], v[108:109]
	v_add_f32_e32 v157, v166, v167
	v_lshlrev_b32_e32 v160, 16, v110
	v_and_b32_e32 v161, 0xffff0000, v110
	v_add_f32_e32 v157, v168, v157
	v_pk_mul_f32 v[170:171], v[160:161], v[160:161]
	v_add_f32_e32 v157, v169, v157
	v_lshlrev_b32_e32 v110, 16, v111
	v_and_b32_e32 v111, 0xffff0000, v111
	v_add_f32_e32 v157, v170, v157
	v_pk_mul_f32 v[172:173], v[110:111], v[110:111]
	v_add_f32_e32 v157, v171, v157
	v_lshlrev_b32_e32 v162, 16, v100
	v_and_b32_e32 v163, 0xffff0000, v100
	v_add_f32_e32 v157, v172, v157
	v_pk_mul_f32 v[174:175], v[162:163], v[162:163]
	v_add_f32_e32 v157, v173, v157
	v_lshlrev_b32_e32 v100, 16, v101
	v_and_b32_e32 v101, 0xffff0000, v101
	v_add_f32_e32 v157, v174, v157
	v_pk_mul_f32 v[176:177], v[100:101], v[100:101]
	v_add_f32_e32 v157, v175, v157
	v_lshlrev_b32_e32 v164, 16, v102
	v_and_b32_e32 v165, 0xffff0000, v102
	v_add_f32_e32 v157, v176, v157
	v_pk_mul_f32 v[178:179], v[164:165], v[164:165]
	v_add_f32_e32 v157, v177, v157
	v_lshlrev_b32_e32 v102, 16, v103
	v_and_b32_e32 v103, 0xffff0000, v103
	v_add_f32_e32 v157, v178, v157
	v_pk_mul_f32 v[180:181], v[102:103], v[102:103]
	v_add_f32_e32 v157, v179, v157
	v_add_f32_e32 v157, v180, v157
	v_add_f32_e32 v157, v181, v157
	ds_bpermute_b32 v166, v113, v157
	v_lshl_add_u64 v[128:129], v[128:129], 0, s[16:17]
	s_waitcnt lgkmcnt(0)
	v_add_f32_e32 v157, v157, v166
	ds_bpermute_b32 v166, v150, v157
	s_waitcnt lgkmcnt(0)
	v_add_f32_e32 v157, v157, v166
	ds_bpermute_b32 v166, v151, v157
	s_waitcnt lgkmcnt(0)
	v_add_f32_e32 v157, v157, v166
	ds_bpermute_b32 v166, v152, v157
	s_waitcnt lgkmcnt(0)
	v_add_f32_e32 v157, v157, v166
	ds_bpermute_b32 v166, v153, v157
	s_waitcnt lgkmcnt(0)
	v_add_f32_e32 v157, v157, v166
	ds_bpermute_b32 v166, v155, v157
	s_waitcnt lgkmcnt(0)
	v_add_f32_e32 v157, v157, v166
	v_fmamk_f32 v157, v157, 0x3a800000, v156
	v_mul_f32_e32 v166, 0x4b800000, v157
	v_cmp_gt_f32_e32 vcc, s28, v157
	s_nop 1
	v_cndmask_b32_e32 v157, v157, v166, vcc
	v_rsq_f32_e32 v157, v157
	s_nop 0
	v_mul_f32_e32 v166, 0x45800000, v157
	v_cndmask_b32_e32 v166, v157, v166, vcc
	v_pk_mul_f32 v[100:101], v[166:167], v[100:101] op_sel_hi:[0,1]
	v_pk_mul_f32 v[100:101], v[18:19], v[100:101]
	v_pk_mul_f32 v[108:109], v[166:167], v[108:109] op_sel_hi:[0,1]
	s_nop 0
	v_pk_fma_f32 v[46:47], v[78:79], v[100:101], v[46:47]
	v_pk_mul_f32 v[100:101], v[166:167], v[164:165] op_sel_hi:[0,1]
	v_pk_mul_f32 v[158:159], v[166:167], v[158:159] op_sel_hi:[0,1]
	v_pk_mul_f32 v[160:161], v[166:167], v[160:161] op_sel_hi:[0,1]
	v_pk_mul_f32 v[108:109], v[2:3], v[108:109]
	v_pk_mul_f32 v[100:101], v[20:21], v[100:101]
	v_pk_mul_f32 v[158:159], v[0:1], v[158:159]
	v_pk_fma_f32 v[62:63], v[38:39], v[108:109], v[62:63]
	v_pk_mul_f32 v[108:109], v[4:5], v[160:161]
	s_nop 0
	v_pk_fma_f32 v[32:33], v[72:73], v[100:101], v[32:33]
	v_pk_mul_f32 v[100:101], v[166:167], v[102:103] op_sel_hi:[0,1]
	v_pk_fma_f32 v[60:61], v[36:37], v[158:159], v[60:61]
	v_pk_fma_f32 v[48:49], v[40:41], v[108:109], v[48:49]
	v_pk_mul_f32 v[108:109], v[166:167], v[110:111] op_sel_hi:[0,1]
	v_pk_mul_f32 v[100:101], v[22:23], v[100:101]
	v_pk_mul_f32 v[108:109], v[6:7], v[108:109]
	v_pk_fma_f32 v[34:35], v[74:75], v[100:101], v[34:35]
	v_pk_mul_f32 v[100:101], v[60:61], v[60:61]
	v_pk_fma_f32 v[50:51], v[42:43], v[108:109], v[50:51]
	v_pk_mul_f32 v[108:109], v[166:167], v[162:163] op_sel_hi:[0,1]
	v_pk_mul_f32 v[102:103], v[62:63], v[62:63]
	v_add_f32_e32 v100, v100, v101
	v_pk_mul_f32 v[108:109], v[16:17], v[108:109]
	v_add_f32_e32 v100, v102, v100
	v_pk_fma_f32 v[44:45], v[76:77], v[108:109], v[44:45]
	v_pk_mul_f32 v[108:109], v[48:49], v[48:49]
	v_add_f32_e32 v100, v103, v100
	v_add_f32_e32 v100, v108, v100
	v_pk_mul_f32 v[110:111], v[50:51], v[50:51]
	v_add_f32_e32 v100, v109, v100
	v_add_f32_e32 v100, v110, v100
	v_pk_mul_f32 v[158:159], v[44:45], v[44:45]
	v_add_f32_e32 v100, v111, v100
	v_add_f32_e32 v100, v158, v100
	v_pk_mul_f32 v[160:161], v[46:47], v[46:47]
	v_add_f32_e32 v100, v159, v100
	v_add_f32_e32 v100, v160, v100
	v_pk_mul_f32 v[162:163], v[32:33], v[32:33]
	v_add_f32_e32 v100, v161, v100
	v_add_f32_e32 v100, v162, v100
	v_pk_mul_f32 v[164:165], v[34:35], v[34:35]
	v_add_f32_e32 v100, v163, v100
	v_add_f32_e32 v100, v164, v100
	v_add_f32_e32 v100, v165, v100
	ds_bpermute_b32 v101, v113, v100
	v_cmp_gt_i32_e32 vcc, s24, v149
	v_mov_b32_e32 v110, s3
	v_mov_b32_e32 v111, s5
	s_waitcnt lgkmcnt(0)
	v_add_f32_e32 v100, v100, v101
	ds_bpermute_b32 v101, v150, v100
	s_waitcnt lgkmcnt(0)
	v_add_f32_e32 v108, v100, v101
	ds_bpermute_b32 v109, v151, v108
	v_lshl_add_u64 v[100:101], v[118:119], 0, s[18:19]
	v_cndmask_b32_e32 v102, v149, v100, vcc
	v_cndmask_b32_e32 v100, v148, v100, vcc
	v_cndmask_b32_e32 v103, 0, v101, vcc
	s_waitcnt lgkmcnt(0)
	v_add_f32_e32 v108, v108, v109
	ds_bpermute_b32 v109, v152, v108
	v_mov_b32_e32 v101, v103
	v_lshlrev_b64 v[100:101], 12, v[100:101]
	v_lshlrev_b64 v[102:103], 11, v[102:103]
	s_add_u32 s18, s18, 0x80
	s_waitcnt lgkmcnt(0)
	v_add_f32_e32 v148, v108, v109
	ds_bpermute_b32 v149, v153, v148
	v_cndmask_b32_e32 v109, v110, v111, vcc
	v_mov_b32_e32 v108, s2
	v_mov_b32_e32 v110, s4
	v_cndmask_b32_e32 v108, v108, v110, vcc
	s_waitcnt lgkmcnt(0)
	v_add_f32_e32 v110, v148, v149
	ds_bpermute_b32 v111, v155, v110
	v_lshl_add_u64 v[100:101], v[108:109], 0, v[100:101]
	v_lshl_add_u64 v[100:101], v[100:101], 0, v[114:115]
	global_store_dwordx4 v[100:101], v[60:63], off
	global_store_dwordx4 v[100:101], v[48:51], off offset:16
	global_store_dwordx4 v[100:101], v[44:47], off offset:2048
	global_store_dwordx4 v[100:101], v[32:35], off offset:2064
	s_waitcnt lgkmcnt(0)
	v_add_f32_e32 v108, v110, v111
	v_fmamk_f32 v108, v108, 0x3a800000, v156
	v_mul_f32_e32 v109, 0x4b800000, v108
	v_cmp_gt_f32_e32 vcc, s28, v108
	s_addc_u32 s19, s19, 0
	s_nop 0
	v_cndmask_b32_e32 v108, v108, v109, vcc
	v_rsq_f32_e32 v108, v108
	s_nop 0
	v_mul_f32_e32 v100, 0x45800000, v108
	v_cndmask_b32_e32 v100, v108, v100, vcc
	v_pk_mul_f32 v[48:49], v[48:49], v[100:101] op_sel_hi:[1,0]
	v_pk_mul_f32 v[60:61], v[60:61], v[100:101] op_sel_hi:[1,0]
	v_pk_mul_f32 v[48:49], v[12:13], v[48:49]
	v_pk_mul_f32 v[62:63], v[62:63], v[100:101] op_sel_hi:[1,0]
	v_pk_fma_f32 v[108:109], v[136:137], v[48:49], v[56:57]
	v_pk_mul_f32 v[48:49], v[50:51], v[100:101] op_sel_hi:[1,0]
	v_pk_mul_f32 v[60:61], v[8:9], v[60:61]
	v_pk_mul_f32 v[62:63], v[10:11], v[62:63]
	v_pk_mul_f32 v[48:49], v[14:15], v[48:49]
	v_pk_fma_f32 v[60:61], v[140:141], v[60:61], v[52:53]
	v_pk_fma_f32 v[62:63], v[138:139], v[62:63], v[54:55]
	v_pk_fma_f32 v[110:111], v[134:135], v[48:49], v[58:59]
	v_pk_mul_f32 v[32:33], v[32:33], v[100:101] op_sel_hi:[1,0]
	v_cvt_pk_bf16_f32 v48, v60, v61
	v_cvt_pk_bf16_f32 v49, v62, v63
	v_cvt_pk_bf16_f32 v50, v108, v109
	v_cvt_pk_bf16_f32 v51, v110, v111
	v_lshl_add_u64 v[60:61], v[124:125], 0, v[102:103]
	v_pk_mul_f32 v[32:33], v[28:29], v[32:33]
	global_store_dwordx4 v[60:61], v[48:51], off
	v_pk_mul_f32 v[44:45], v[44:45], v[100:101] op_sel_hi:[1,0]
	v_pk_mul_f32 v[46:47], v[46:47], v[100:101] op_sel_hi:[1,0]
	v_pk_fma_f32 v[48:49], v[142:143], v[32:33], v[88:89]
	v_pk_mul_f32 v[32:33], v[34:35], v[100:101] op_sel_hi:[1,0]
	v_pk_mul_f32 v[44:45], v[24:25], v[44:45]
	v_pk_mul_f32 v[46:47], v[26:27], v[46:47]
	v_pk_mul_f32 v[32:33], v[30:31], v[32:33]
	v_pk_fma_f32 v[44:45], v[132:133], v[44:45], v[92:93]
	v_pk_fma_f32 v[46:47], v[144:145], v[46:47], v[94:95]
	v_pk_fma_f32 v[50:51], v[146:147], v[32:33], v[90:91]
	v_cvt_pk_bf16_f32 v32, v44, v45
	v_cvt_pk_bf16_f32 v33, v46, v47
	v_cvt_pk_bf16_f32 v34, v48, v49
	v_cvt_pk_bf16_f32 v35, v50, v51
	global_store_dwordx4 v[60:61], v[32:35], off offset:1024
	s_waitcnt vmcnt(6)
	v_mov_b64_e32 v[44:45], v[80:81]
	v_mov_b64_e32 v[48:49], v[68:69]
	v_add_u32_e32 v32, s18, v116
	v_add_u32_e32 v32, 0x7f80, v32
	v_cmp_lt_i32_e32 vcc, s29, v32
	v_mov_b64_e32 v[32:33], v[84:85]
	v_mov_b64_e32 v[60:61], v[64:65]
	v_mov_b64_e32 v[100:101], v[104:105]
	v_mov_b64_e32 v[110:111], v[98:99]
	s_or_b64 s[10:11], vcc, s[10:11]
	v_mov_b64_e32 v[34:35], v[86:87]
	v_mov_b64_e32 v[46:47], v[82:83]
	v_mov_b64_e32 v[50:51], v[70:71]
	v_mov_b64_e32 v[62:63], v[66:67]
	v_mov_b64_e32 v[102:103], v[106:107]
	v_mov_b64_e32 v[108:109], v[96:97]
	s_andn2_b64 exec, exec, s[10:11]
	s_cbranch_execz .LBB0_1368

.LBB0_1366:
	s_or_b64 exec, exec, s[20:21]
	v_min_i32_e32 v114, 0x8000, v149
	v_ashrrev_i32_e32 v157, 13, v114
	v_cmp_ne_u32_e32 vcc, v157, v131
	v_lshlrev_b32_e32 v114, 2, v112
	s_and_saveexec_b64 s[20:21], vcc
	s_cbranch_execz .LBB0_1359
	v_mul_hi_i32_i24_e32 v53, 0x3000, v157
	v_mul_i32_i24_e32 v52, 0x3000, v157
	v_lshl_add_u64 v[36:37], s[6:7], 0, v[52:53]
	v_lshl_add_u64 v[74:75], v[122:123], 0, v[52:53]
	v_lshl_add_u64 v[72:73], v[36:37], 0, s[12:13]
	v_add_co_u32_e32 v78, vcc, s27, v74
	v_lshl_add_u64 v[54:55], v[72:73], 0, v[114:115]
	s_nop 0
	v_addc_co_u32_e32 v79, vcc, 0, v75, vcc
	global_load_dwordx4 v[36:39], v[54:55], off
	global_load_dwordx4 v[40:43], v[54:55], off offset:16
	s_nop 0
	global_load_dwordx4 v[52:55], v[74:75], off
	global_load_dwordx4 v[56:59], v[74:75], off offset:16
	v_lshl_add_u64 v[76:77], v[74:75], 0, s[8:9]
	global_load_dwordx4 v[132:135], v[78:79], off
	global_load_dwordx4 v[142:145], v[76:77], off offset:16
	v_mov_b32_e32 v131, v115
	v_lshl_add_u64 v[72:73], v[72:73], 0, v[130:131]
	v_lshl_add_u64 v[76:77], v[74:75], 0, s[14:15]
	global_load_dwordx4 v[158:161], v[78:79], off offset:2048
	global_load_dwordx4 v[162:165], v[76:77], off offset:16
	global_load_dwordx4 v[92:95], v[74:75], off offset:2048
	global_load_dwordx4 v[88:91], v[74:75], off offset:2064
	s_nop 0
	global_load_dwordx4 v[76:79], v[72:73], off
	s_nop 0
	global_load_dwordx4 v[72:75], v[72:73], off offset:16
	v_mov_b32_e32 v131, v157
	s_waitcnt vmcnt(7)
	v_pk_add_f32 v[140:141], v[132:133], 1.0 op_sel_hi:[1,0]
	v_pk_add_f32 v[138:139], v[134:135], 1.0 op_sel_hi:[1,0]
	s_waitcnt vmcnt(6)
	v_pk_add_f32 v[136:137], v[142:143], 1.0 op_sel_hi:[1,0]
	v_pk_add_f32 v[134:135], v[144:145], 1.0 op_sel_hi:[1,0]
	s_waitcnt vmcnt(5)
	v_pk_add_f32 v[132:133], v[158:159], 1.0 op_sel_hi:[1,0]
	v_pk_add_f32 v[144:145], v[160:161], 1.0 op_sel_hi:[1,0]
	s_waitcnt vmcnt(0)
	v_pk_add_f32 v[142:143], v[162:163], 1.0 op_sel_hi:[1,0]
	v_pk_add_f32 v[146:147], v[164:165], 1.0 op_sel_hi:[1,0]
	s_branch .LBB0_1359

.LBB0_1812:
	s_or_b64 exec, exec, s[22:23]
	v_lshlrev_b32_e32 v156, 16, v108
	v_and_b32_e32 v157, 0xffff0000, v108
	v_lshlrev_b32_e32 v108, 16, v109
	v_and_b32_e32 v109, 0xffff0000, v109
	v_pk_mul_f32 v[164:165], v[156:157], v[156:157]
	v_pk_mul_f32 v[166:167], v[108:109], v[108:109]
	v_add_f32_e32 v164, v164, v165
	v_lshlrev_b32_e32 v158, 16, v110
	v_and_b32_e32 v159, 0xffff0000, v110
	v_add_f32_e32 v164, v166, v164
	v_pk_mul_f32 v[168:169], v[158:159], v[158:159]
	v_add_f32_e32 v164, v167, v164
	v_lshlrev_b32_e32 v110, 16, v111
	v_and_b32_e32 v111, 0xffff0000, v111
	v_add_f32_e32 v164, v168, v164
	v_pk_mul_f32 v[170:171], v[110:111], v[110:111]
	v_add_f32_e32 v164, v169, v164
	v_lshlrev_b32_e32 v160, 16, v96
	v_and_b32_e32 v161, 0xffff0000, v96
	v_add_f32_e32 v164, v170, v164
	v_pk_mul_f32 v[172:173], v[160:161], v[160:161]
	v_add_f32_e32 v164, v171, v164
	v_lshlrev_b32_e32 v96, 16, v97
	v_and_b32_e32 v97, 0xffff0000, v97
	v_add_f32_e32 v164, v172, v164
	v_pk_mul_f32 v[174:175], v[96:97], v[96:97]
	v_add_f32_e32 v164, v173, v164
	v_lshlrev_b32_e32 v162, 16, v98
	v_and_b32_e32 v163, 0xffff0000, v98
	v_add_f32_e32 v164, v174, v164
	v_pk_mul_f32 v[176:177], v[162:163], v[162:163]
	v_add_f32_e32 v164, v175, v164
	v_lshlrev_b32_e32 v98, 16, v99
	v_and_b32_e32 v99, 0xffff0000, v99
	v_add_f32_e32 v164, v176, v164
	v_pk_mul_f32 v[178:179], v[98:99], v[98:99]
	v_add_f32_e32 v164, v177, v164
	v_add_f32_e32 v164, v178, v164
	v_add_f32_e32 v164, v179, v164
	ds_bpermute_b32 v165, v147, v164
	s_and_b64 s[2:3], exec, s[2:3]
	s_or_b64 s[10:11], s[2:3], s[10:11]
	v_lshl_add_u64 v[124:125], v[124:125], 0, s[20:21]
	v_lshl_add_u64 v[126:127], v[126:127], 0, s[18:19]
	s_waitcnt lgkmcnt(0)
	v_add_f32_e32 v164, v164, v165
	ds_bpermute_b32 v165, v148, v164
	s_waitcnt lgkmcnt(0)
	v_add_f32_e32 v164, v164, v165
	ds_bpermute_b32 v165, v149, v164
	s_waitcnt lgkmcnt(0)
	v_add_f32_e32 v164, v164, v165
	ds_bpermute_b32 v165, v150, v164
	s_waitcnt lgkmcnt(0)
	v_add_f32_e32 v164, v164, v165
	ds_bpermute_b32 v165, v151, v164
	s_waitcnt lgkmcnt(0)
	v_add_f32_e32 v164, v164, v165
	ds_bpermute_b32 v165, v152, v164
	s_waitcnt lgkmcnt(0)
	v_add_f32_e32 v164, v164, v165
	v_fmamk_f32 v164, v164, 0x3a800000, v155
	v_mul_f32_e32 v165, 0x4b800000, v164
	v_cmp_gt_f32_e32 vcc, s27, v164
	s_nop 1
	v_cndmask_b32_e32 v164, v164, v165, vcc
	v_rsq_f32_e32 v164, v164
	s_nop 0
	v_mul_f32_e32 v165, 0x45800000, v164
	v_cndmask_b32_e32 v164, v164, v165, vcc
	v_pk_mul_f32 v[96:97], v[164:165], v[96:97] op_sel_hi:[0,1]
	v_pk_mul_f32 v[96:97], v[10:11], v[96:97]
	v_pk_mul_f32 v[108:109], v[164:165], v[108:109] op_sel_hi:[0,1]
	s_nop 0
	v_pk_fma_f32 v[38:39], v[94:95], v[96:97], v[38:39]
	v_pk_mul_f32 v[96:97], v[164:165], v[162:163] op_sel_hi:[0,1]
	v_pk_mul_f32 v[156:157], v[164:165], v[156:157] op_sel_hi:[0,1]
	v_pk_mul_f32 v[158:159], v[164:165], v[158:159] op_sel_hi:[0,1]
	v_pk_mul_f32 v[108:109], v[26:27], v[108:109]
	v_pk_mul_f32 v[96:97], v[12:13], v[96:97]
	v_pk_mul_f32 v[156:157], v[24:25], v[156:157]
	v_pk_fma_f32 v[46:47], v[50:51], v[108:109], v[46:47]
	v_pk_mul_f32 v[108:109], v[28:29], v[158:159]
	s_nop 0
	v_pk_fma_f32 v[32:33], v[88:89], v[96:97], v[32:33]
	v_pk_mul_f32 v[96:97], v[164:165], v[98:99] op_sel_hi:[0,1]
	v_pk_fma_f32 v[44:45], v[48:49], v[156:157], v[44:45]
	v_pk_fma_f32 v[40:41], v[52:53], v[108:109], v[40:41]
	v_pk_mul_f32 v[108:109], v[164:165], v[110:111] op_sel_hi:[0,1]
	v_pk_mul_f32 v[96:97], v[14:15], v[96:97]
	v_pk_mul_f32 v[108:109], v[30:31], v[108:109]
	v_pk_fma_f32 v[34:35], v[90:91], v[96:97], v[34:35]
	v_pk_mul_f32 v[96:97], v[44:45], v[44:45]
	v_pk_fma_f32 v[42:43], v[54:55], v[108:109], v[42:43]
	v_pk_mul_f32 v[108:109], v[164:165], v[160:161] op_sel_hi:[0,1]
	v_pk_mul_f32 v[98:99], v[46:47], v[46:47]
	v_add_f32_e32 v96, v96, v97
	v_pk_mul_f32 v[108:109], v[8:9], v[108:109]
	v_add_f32_e32 v96, v98, v96
	v_pk_fma_f32 v[36:37], v[92:93], v[108:109], v[36:37]
	v_pk_mul_f32 v[108:109], v[40:41], v[40:41]
	v_add_f32_e32 v96, v99, v96
	v_add_f32_e32 v96, v108, v96
	v_pk_mul_f32 v[110:111], v[42:43], v[42:43]
	v_add_f32_e32 v96, v109, v96
	v_add_f32_e32 v96, v110, v96
	v_pk_mul_f32 v[156:157], v[36:37], v[36:37]
	v_add_f32_e32 v96, v111, v96
	v_add_f32_e32 v96, v156, v96
	v_pk_mul_f32 v[158:159], v[38:39], v[38:39]
	v_add_f32_e32 v96, v157, v96
	v_add_f32_e32 v96, v158, v96
	v_pk_mul_f32 v[160:161], v[32:33], v[32:33]
	v_add_f32_e32 v96, v159, v96
	v_add_f32_e32 v96, v160, v96
	v_pk_mul_f32 v[162:163], v[34:35], v[34:35]
	v_add_f32_e32 v96, v161, v96
	v_add_f32_e32 v96, v162, v96
	v_add_f32_e32 v96, v163, v96
	ds_bpermute_b32 v97, v147, v96
	s_waitcnt lgkmcnt(0)
	v_add_f32_e32 v96, v96, v97
	ds_bpermute_b32 v97, v148, v96
	s_waitcnt lgkmcnt(0)
	v_add_f32_e32 v96, v96, v97
	ds_bpermute_b32 v97, v149, v96
	s_waitcnt lgkmcnt(0)
	v_add_f32_e32 v96, v96, v97
	ds_bpermute_b32 v97, v150, v96
	s_waitcnt lgkmcnt(0)
	v_add_f32_e32 v96, v96, v97
	ds_bpermute_b32 v97, v151, v96
	s_waitcnt lgkmcnt(0)
	v_add_f32_e32 v98, v96, v97
	ds_bpermute_b32 v99, v152, v98
	v_lshl_add_u64 v[96:97], v[114:115], 0, v[122:123]
	global_store_dwordx4 v[96:97], v[44:47], off
	global_store_dwordx4 v[96:97], v[40:43], off offset:16
	global_store_dwordx4 v[96:97], v[36:39], off offset:2048
	global_store_dwordx4 v[96:97], v[32:35], off offset:2064
	v_lshl_add_u64 v[114:115], v[114:115], 0, s[20:21]
	s_waitcnt lgkmcnt(0)
	v_add_f32_e32 v98, v98, v99
	v_fmamk_f32 v98, v98, 0x3a800000, v155
	v_mul_f32_e32 v99, 0x4b800000, v98
	v_cmp_gt_f32_e32 vcc, s27, v98
	s_nop 1
	v_cndmask_b32_e32 v98, v98, v99, vcc
	v_rsq_f32_e32 v98, v98
	s_nop 0
	v_mul_f32_e32 v96, 0x45800000, v98
	v_cndmask_b32_e32 v96, v98, v96, vcc
	v_pk_mul_f32 v[40:41], v[40:41], v[96:97] op_sel_hi:[1,0]
	v_pk_mul_f32 v[44:45], v[44:45], v[96:97] op_sel_hi:[1,0]
	v_pk_mul_f32 v[40:41], v[20:21], v[40:41]
	v_pk_mul_f32 v[44:45], v[16:17], v[44:45]
	v_pk_fma_f32 v[98:99], v[134:135], v[40:41], v[68:69]
	v_pk_mul_f32 v[40:41], v[42:43], v[96:97] op_sel_hi:[1,0]
	v_pk_fma_f32 v[44:45], v[138:139], v[44:45], v[64:65]
	v_pk_mul_f32 v[46:47], v[46:47], v[96:97] op_sel_hi:[1,0]
	v_pk_mul_f32 v[40:41], v[22:23], v[40:41]
	v_pk_mul_f32 v[46:47], v[18:19], v[46:47]
	v_pk_fma_f32 v[108:109], v[132:133], v[40:41], v[70:71]
	v_cvt_pk_bf16_f32 v40, v44, v45
	v_lshl_add_u64 v[44:45], v[116:117], 0, v[120:121]
	v_pk_fma_f32 v[46:47], v[136:137], v[46:47], v[66:67]
	v_add_co_u32_e32 v44, vcc, s34, v44
	v_pk_mul_f32 v[32:33], v[32:33], v[96:97] op_sel_hi:[1,0]
	v_cvt_pk_bf16_f32 v41, v46, v47
	v_cvt_pk_bf16_f32 v42, v98, v99
	v_cvt_pk_bf16_f32 v43, v108, v109
	v_addc_co_u32_e32 v45, vcc, 0, v45, vcc
	v_pk_mul_f32 v[32:33], v[4:5], v[32:33]
	global_store_dwordx4 v[44:45], v[40:43], off
	v_pk_mul_f32 v[36:37], v[36:37], v[96:97] op_sel_hi:[1,0]
	v_pk_mul_f32 v[38:39], v[38:39], v[96:97] op_sel_hi:[1,0]
	v_pk_fma_f32 v[40:41], v[140:141], v[32:33], v[100:101]
	v_pk_mul_f32 v[32:33], v[34:35], v[96:97] op_sel_hi:[1,0]
	v_pk_mul_f32 v[36:37], v[0:1], v[36:37]
	v_pk_mul_f32 v[38:39], v[2:3], v[38:39]
	v_pk_mul_f32 v[32:33], v[6:7], v[32:33]
	v_pk_fma_f32 v[36:37], v[130:131], v[36:37], v[104:105]
	v_pk_fma_f32 v[38:39], v[142:143], v[38:39], v[106:107]
	v_pk_fma_f32 v[42:43], v[144:145], v[32:33], v[102:103]
	v_cvt_pk_bf16_f32 v32, v36, v37
	v_cvt_pk_bf16_f32 v33, v38, v39
	v_cvt_pk_bf16_f32 v34, v40, v41
	v_cvt_pk_bf16_f32 v35, v42, v43
	global_store_dwordx4 v[44:45], v[32:35], off offset:1024
	s_waitcnt vmcnt(6)
	v_mov_b64_e32 v[36:37], v[76:77]
	v_mov_b64_e32 v[40:41], v[56:57]
	v_mov_b64_e32 v[32:33], v[72:73]
	v_mov_b64_e32 v[44:45], v[60:61]
	v_mov_b64_e32 v[98:99], v[82:83]
	v_mov_b64_e32 v[110:111], v[86:87]
	v_lshl_add_u64 v[116:117], v[116:117], 0, s[18:19]
	v_mov_b64_e32 v[34:35], v[74:75]
	v_mov_b64_e32 v[38:39], v[78:79]
	v_mov_b64_e32 v[42:43], v[58:59]
	v_mov_b64_e32 v[46:47], v[62:63]
	v_mov_b64_e32 v[96:97], v[80:81]
	v_mov_b64_e32 v[108:109], v[84:85]
	s_andn2_b64 exec, exec, s[10:11]
	s_cbranch_execz .LBB0_1817

.LBB0_1815:
	s_or_b64 exec, exec, s[22:23]
	v_ashrrev_i32_e32 v156, 13, v153
	v_cmp_ne_u32_e32 vcc, v156, v129
	s_and_saveexec_b64 s[22:23], vcc
	s_cbranch_execz .LBB0_1812
	v_mul_hi_i32_i24_e32 v65, 0x3000, v156
	v_mul_i32_i24_e32 v64, 0x3000, v156
	v_lshl_add_u64 v[48:49], s[6:7], 0, v[64:65]
	v_lshl_add_u64 v[90:91], v[118:119], 0, v[64:65]
	v_lshl_add_u64 v[88:89], v[48:49], 0, s[12:13]
	v_add_co_u32_e32 v94, vcc, s26, v90
	v_lshl_add_u64 v[66:67], v[88:89], 0, v[112:113]
	s_nop 0
	v_addc_co_u32_e32 v95, vcc, 0, v91, vcc
	global_load_dwordx4 v[48:51], v[66:67], off
	global_load_dwordx4 v[52:55], v[66:67], off offset:16
	s_nop 0
	global_load_dwordx4 v[64:67], v[90:91], off
	global_load_dwordx4 v[68:71], v[90:91], off offset:16
	v_lshl_add_u64 v[92:93], v[90:91], 0, s[14:15]
	global_load_dwordx4 v[130:133], v[94:95], off
	global_load_dwordx4 v[140:143], v[92:93], off offset:16
	v_mov_b32_e32 v129, v113
	v_lshl_add_u64 v[88:89], v[88:89], 0, v[128:129]
	v_lshl_add_u64 v[92:93], v[90:91], 0, s[16:17]
	global_load_dwordx4 v[158:161], v[94:95], off offset:2048
	global_load_dwordx4 v[162:165], v[92:93], off offset:16
	global_load_dwordx4 v[104:107], v[90:91], off offset:2048
	global_load_dwordx4 v[100:103], v[90:91], off offset:2064
	s_nop 0
	global_load_dwordx4 v[92:95], v[88:89], off
	s_nop 0
	global_load_dwordx4 v[88:91], v[88:89], off offset:16
	v_mov_b32_e32 v129, v156
	s_waitcnt vmcnt(7)
	v_pk_add_f32 v[138:139], v[130:131], 1.0 op_sel_hi:[1,0]
	v_pk_add_f32 v[136:137], v[132:133], 1.0 op_sel_hi:[1,0]
	s_waitcnt vmcnt(6)
	v_pk_add_f32 v[134:135], v[140:141], 1.0 op_sel_hi:[1,0]
	v_pk_add_f32 v[132:133], v[142:143], 1.0 op_sel_hi:[1,0]
	s_waitcnt vmcnt(5)
	v_pk_add_f32 v[130:131], v[158:159], 1.0 op_sel_hi:[1,0]
	v_pk_add_f32 v[142:143], v[160:161], 1.0 op_sel_hi:[1,0]
	s_waitcnt vmcnt(0)
	v_pk_add_f32 v[140:141], v[162:163], 1.0 op_sel_hi:[1,0]
	v_pk_add_f32 v[144:145], v[164:165], 1.0 op_sel_hi:[1,0]
	s_branch .LBB0_1812

.LBB0_1855:
	s_or_b64 exec, exec, s[20:21]
	v_lshlrev_b32_e32 v158, 16, v108
	v_and_b32_e32 v159, 0xffff0000, v108
	v_lshlrev_b32_e32 v108, 16, v109
	v_and_b32_e32 v109, 0xffff0000, v109
	v_pk_mul_f32 v[166:167], v[158:159], v[158:159]
	v_pk_mul_f32 v[168:169], v[108:109], v[108:109]
	v_add_f32_e32 v157, v166, v167
	v_lshlrev_b32_e32 v160, 16, v110
	v_and_b32_e32 v161, 0xffff0000, v110
	v_add_f32_e32 v157, v168, v157
	v_pk_mul_f32 v[170:171], v[160:161], v[160:161]
	v_add_f32_e32 v157, v169, v157
	v_lshlrev_b32_e32 v110, 16, v111
	v_and_b32_e32 v111, 0xffff0000, v111
	v_add_f32_e32 v157, v170, v157
	v_pk_mul_f32 v[172:173], v[110:111], v[110:111]
	v_add_f32_e32 v157, v171, v157
	v_lshlrev_b32_e32 v162, 16, v100
	v_and_b32_e32 v163, 0xffff0000, v100
	v_add_f32_e32 v157, v172, v157
	v_pk_mul_f32 v[174:175], v[162:163], v[162:163]
	v_add_f32_e32 v157, v173, v157
	v_lshlrev_b32_e32 v100, 16, v101
	v_and_b32_e32 v101, 0xffff0000, v101
	v_add_f32_e32 v157, v174, v157
	v_pk_mul_f32 v[176:177], v[100:101], v[100:101]
	v_add_f32_e32 v157, v175, v157
	v_lshlrev_b32_e32 v164, 16, v102
	v_and_b32_e32 v165, 0xffff0000, v102
	v_add_f32_e32 v157, v176, v157
	v_pk_mul_f32 v[178:179], v[164:165], v[164:165]
	v_add_f32_e32 v157, v177, v157
	v_lshlrev_b32_e32 v102, 16, v103
	v_and_b32_e32 v103, 0xffff0000, v103
	v_add_f32_e32 v157, v178, v157
	v_pk_mul_f32 v[180:181], v[102:103], v[102:103]
	v_add_f32_e32 v157, v179, v157
	v_add_f32_e32 v157, v180, v157
	v_add_f32_e32 v157, v181, v157
	ds_bpermute_b32 v166, v113, v157
	v_lshl_add_u64 v[128:129], v[128:129], 0, s[16:17]
	s_waitcnt lgkmcnt(0)
	v_add_f32_e32 v157, v157, v166
	ds_bpermute_b32 v166, v150, v157
	s_waitcnt lgkmcnt(0)
	v_add_f32_e32 v157, v157, v166
	ds_bpermute_b32 v166, v151, v157
	s_waitcnt lgkmcnt(0)
	v_add_f32_e32 v157, v157, v166
	ds_bpermute_b32 v166, v152, v157
	s_waitcnt lgkmcnt(0)
	v_add_f32_e32 v157, v157, v166
	ds_bpermute_b32 v166, v153, v157
	s_waitcnt lgkmcnt(0)
	v_add_f32_e32 v157, v157, v166
	ds_bpermute_b32 v166, v155, v157
	s_waitcnt lgkmcnt(0)
	v_add_f32_e32 v157, v157, v166
	v_fmamk_f32 v157, v157, 0x3a800000, v156
	v_mul_f32_e32 v166, 0x4b800000, v157
	v_cmp_gt_f32_e32 vcc, s28, v157
	s_nop 1
	v_cndmask_b32_e32 v157, v157, v166, vcc
	v_rsq_f32_e32 v157, v157
	s_nop 0
	v_mul_f32_e32 v166, 0x45800000, v157
	v_cndmask_b32_e32 v166, v157, v166, vcc
	v_pk_mul_f32 v[100:101], v[166:167], v[100:101] op_sel_hi:[0,1]
	v_pk_mul_f32 v[100:101], v[18:19], v[100:101]
	v_pk_mul_f32 v[108:109], v[166:167], v[108:109] op_sel_hi:[0,1]
	s_nop 0
	v_pk_fma_f32 v[46:47], v[78:79], v[100:101], v[46:47]
	v_pk_mul_f32 v[100:101], v[166:167], v[164:165] op_sel_hi:[0,1]
	v_pk_mul_f32 v[158:159], v[166:167], v[158:159] op_sel_hi:[0,1]
	v_pk_mul_f32 v[160:161], v[166:167], v[160:161] op_sel_hi:[0,1]
	v_pk_mul_f32 v[108:109], v[2:3], v[108:109]
	v_pk_mul_f32 v[100:101], v[20:21], v[100:101]
	v_pk_mul_f32 v[158:159], v[0:1], v[158:159]
	v_pk_fma_f32 v[62:63], v[38:39], v[108:109], v[62:63]
	v_pk_mul_f32 v[108:109], v[4:5], v[160:161]
	s_nop 0
	v_pk_fma_f32 v[32:33], v[72:73], v[100:101], v[32:33]
	v_pk_mul_f32 v[100:101], v[166:167], v[102:103] op_sel_hi:[0,1]
	v_pk_fma_f32 v[60:61], v[36:37], v[158:159], v[60:61]
	v_pk_fma_f32 v[48:49], v[40:41], v[108:109], v[48:49]
	v_pk_mul_f32 v[108:109], v[166:167], v[110:111] op_sel_hi:[0,1]
	v_pk_mul_f32 v[100:101], v[22:23], v[100:101]
	v_pk_mul_f32 v[108:109], v[6:7], v[108:109]
	v_pk_fma_f32 v[34:35], v[74:75], v[100:101], v[34:35]
	v_pk_mul_f32 v[100:101], v[60:61], v[60:61]
	v_pk_fma_f32 v[50:51], v[42:43], v[108:109], v[50:51]
	v_pk_mul_f32 v[108:109], v[166:167], v[162:163] op_sel_hi:[0,1]
	v_pk_mul_f32 v[102:103], v[62:63], v[62:63]
	v_add_f32_e32 v100, v100, v101
	v_pk_mul_f32 v[108:109], v[16:17], v[108:109]
	v_add_f32_e32 v100, v102, v100
	v_pk_fma_f32 v[44:45], v[76:77], v[108:109], v[44:45]
	v_pk_mul_f32 v[108:109], v[48:49], v[48:49]
	v_add_f32_e32 v100, v103, v100
	v_add_f32_e32 v100, v108, v100
	v_pk_mul_f32 v[110:111], v[50:51], v[50:51]
	v_add_f32_e32 v100, v109, v100
	v_add_f32_e32 v100, v110, v100
	v_pk_mul_f32 v[158:159], v[44:45], v[44:45]
	v_add_f32_e32 v100, v111, v100
	v_add_f32_e32 v100, v158, v100
	v_pk_mul_f32 v[160:161], v[46:47], v[46:47]
	v_add_f32_e32 v100, v159, v100
	v_add_f32_e32 v100, v160, v100
	v_pk_mul_f32 v[162:163], v[32:33], v[32:33]
	v_add_f32_e32 v100, v161, v100
	v_add_f32_e32 v100, v162, v100
	v_pk_mul_f32 v[164:165], v[34:35], v[34:35]
	v_add_f32_e32 v100, v163, v100
	v_add_f32_e32 v100, v164, v100
	v_add_f32_e32 v100, v165, v100
	ds_bpermute_b32 v101, v113, v100
	v_cmp_gt_i32_e32 vcc, s24, v149
	v_mov_b32_e32 v110, s3
	v_mov_b32_e32 v111, s5
	s_waitcnt lgkmcnt(0)
	v_add_f32_e32 v100, v100, v101
	ds_bpermute_b32 v101, v150, v100
	s_waitcnt lgkmcnt(0)
	v_add_f32_e32 v108, v100, v101
	ds_bpermute_b32 v109, v151, v108
	v_lshl_add_u64 v[100:101], v[118:119], 0, s[18:19]
	v_cndmask_b32_e32 v102, v149, v100, vcc
	v_cndmask_b32_e32 v100, v148, v100, vcc
	v_cndmask_b32_e32 v103, 0, v101, vcc
	s_waitcnt lgkmcnt(0)
	v_add_f32_e32 v108, v108, v109
	ds_bpermute_b32 v109, v152, v108
	v_mov_b32_e32 v101, v103
	v_lshlrev_b64 v[100:101], 12, v[100:101]
	v_lshlrev_b64 v[102:103], 11, v[102:103]
	s_add_u32 s18, s18, 0x80
	s_waitcnt lgkmcnt(0)
	v_add_f32_e32 v148, v108, v109
	ds_bpermute_b32 v149, v153, v148
	v_cndmask_b32_e32 v109, v110, v111, vcc
	v_mov_b32_e32 v108, s2
	v_mov_b32_e32 v110, s4
	v_cndmask_b32_e32 v108, v108, v110, vcc
	s_waitcnt lgkmcnt(0)
	v_add_f32_e32 v110, v148, v149
	ds_bpermute_b32 v111, v155, v110
	v_lshl_add_u64 v[100:101], v[108:109], 0, v[100:101]
	v_lshl_add_u64 v[100:101], v[100:101], 0, v[114:115]
	global_store_dwordx4 v[100:101], v[60:63], off
	global_store_dwordx4 v[100:101], v[48:51], off offset:16
	global_store_dwordx4 v[100:101], v[44:47], off offset:2048
	global_store_dwordx4 v[100:101], v[32:35], off offset:2064
	s_waitcnt lgkmcnt(0)
	v_add_f32_e32 v108, v110, v111
	v_fmamk_f32 v108, v108, 0x3a800000, v156
	v_mul_f32_e32 v109, 0x4b800000, v108
	v_cmp_gt_f32_e32 vcc, s28, v108
	s_addc_u32 s19, s19, 0
	s_nop 0
	v_cndmask_b32_e32 v108, v108, v109, vcc
	v_rsq_f32_e32 v108, v108
	s_nop 0
	v_mul_f32_e32 v100, 0x45800000, v108
	v_cndmask_b32_e32 v100, v108, v100, vcc
	v_pk_mul_f32 v[48:49], v[48:49], v[100:101] op_sel_hi:[1,0]
	v_pk_mul_f32 v[60:61], v[60:61], v[100:101] op_sel_hi:[1,0]
	v_pk_mul_f32 v[48:49], v[12:13], v[48:49]
	v_pk_mul_f32 v[62:63], v[62:63], v[100:101] op_sel_hi:[1,0]
	v_pk_fma_f32 v[108:109], v[136:137], v[48:49], v[56:57]
	v_pk_mul_f32 v[48:49], v[50:51], v[100:101] op_sel_hi:[1,0]
	v_pk_mul_f32 v[60:61], v[8:9], v[60:61]
	v_pk_mul_f32 v[62:63], v[10:11], v[62:63]
	v_pk_mul_f32 v[48:49], v[14:15], v[48:49]
	v_pk_fma_f32 v[60:61], v[140:141], v[60:61], v[52:53]
	v_pk_fma_f32 v[62:63], v[138:139], v[62:63], v[54:55]
	v_pk_fma_f32 v[110:111], v[134:135], v[48:49], v[58:59]
	v_pk_mul_f32 v[32:33], v[32:33], v[100:101] op_sel_hi:[1,0]
	v_cvt_pk_bf16_f32 v48, v60, v61
	v_cvt_pk_bf16_f32 v49, v62, v63
	v_cvt_pk_bf16_f32 v50, v108, v109
	v_cvt_pk_bf16_f32 v51, v110, v111
	v_lshl_add_u64 v[60:61], v[124:125], 0, v[102:103]
	v_pk_mul_f32 v[32:33], v[28:29], v[32:33]
	global_store_dwordx4 v[60:61], v[48:51], off
	v_pk_mul_f32 v[44:45], v[44:45], v[100:101] op_sel_hi:[1,0]
	v_pk_mul_f32 v[46:47], v[46:47], v[100:101] op_sel_hi:[1,0]
	v_pk_fma_f32 v[48:49], v[142:143], v[32:33], v[88:89]
	v_pk_mul_f32 v[32:33], v[34:35], v[100:101] op_sel_hi:[1,0]
	v_pk_mul_f32 v[44:45], v[24:25], v[44:45]
	v_pk_mul_f32 v[46:47], v[26:27], v[46:47]
	v_pk_mul_f32 v[32:33], v[30:31], v[32:33]
	v_pk_fma_f32 v[44:45], v[132:133], v[44:45], v[92:93]
	v_pk_fma_f32 v[46:47], v[144:145], v[46:47], v[94:95]
	v_pk_fma_f32 v[50:51], v[146:147], v[32:33], v[90:91]
	v_cvt_pk_bf16_f32 v32, v44, v45
	v_cvt_pk_bf16_f32 v33, v46, v47
	v_cvt_pk_bf16_f32 v34, v48, v49
	v_cvt_pk_bf16_f32 v35, v50, v51
	global_store_dwordx4 v[60:61], v[32:35], off offset:1024
	s_waitcnt vmcnt(6)
	v_mov_b64_e32 v[44:45], v[80:81]
	v_mov_b64_e32 v[48:49], v[68:69]
	v_add_u32_e32 v32, s18, v116
	v_add_u32_e32 v32, 0x7f80, v32
	v_cmp_lt_i32_e32 vcc, s29, v32
	v_mov_b64_e32 v[32:33], v[84:85]
	v_mov_b64_e32 v[60:61], v[64:65]
	v_mov_b64_e32 v[100:101], v[104:105]
	v_mov_b64_e32 v[110:111], v[98:99]
	s_or_b64 s[8:9], vcc, s[8:9]
	v_mov_b64_e32 v[34:35], v[86:87]
	v_mov_b64_e32 v[46:47], v[82:83]
	v_mov_b64_e32 v[50:51], v[70:71]
	v_mov_b64_e32 v[62:63], v[66:67]
	v_mov_b64_e32 v[102:103], v[106:107]
	v_mov_b64_e32 v[108:109], v[96:97]
	s_andn2_b64 exec, exec, s[8:9]
	s_cbranch_execz .LBB0_1864

.LBB0_1862:
	s_or_b64 exec, exec, s[20:21]
	v_min_i32_e32 v114, 0x8000, v149
	v_ashrrev_i32_e32 v157, 13, v114
	v_cmp_ne_u32_e32 vcc, v157, v131
	v_lshlrev_b32_e32 v114, 2, v112
	s_and_saveexec_b64 s[20:21], vcc
	s_cbranch_execz .LBB0_1855
	v_mul_hi_i32_i24_e32 v53, 0x3000, v157
	v_mul_i32_i24_e32 v52, 0x3000, v157
	v_lshl_add_u64 v[36:37], s[6:7], 0, v[52:53]
	v_lshl_add_u64 v[74:75], v[122:123], 0, v[52:53]
	v_lshl_add_u64 v[72:73], v[36:37], 0, s[10:11]
	v_add_co_u32_e32 v78, vcc, s27, v74
	v_lshl_add_u64 v[54:55], v[72:73], 0, v[114:115]
	s_nop 0
	v_addc_co_u32_e32 v79, vcc, 0, v75, vcc
	global_load_dwordx4 v[36:39], v[54:55], off
	global_load_dwordx4 v[40:43], v[54:55], off offset:16
	s_nop 0
	global_load_dwordx4 v[52:55], v[74:75], off
	global_load_dwordx4 v[56:59], v[74:75], off offset:16
	v_lshl_add_u64 v[76:77], v[74:75], 0, s[12:13]
	global_load_dwordx4 v[132:135], v[78:79], off
	global_load_dwordx4 v[142:145], v[76:77], off offset:16
	v_mov_b32_e32 v131, v115
	v_lshl_add_u64 v[72:73], v[72:73], 0, v[130:131]
	v_lshl_add_u64 v[76:77], v[74:75], 0, s[14:15]
	global_load_dwordx4 v[158:161], v[78:79], off offset:2048
	global_load_dwordx4 v[162:165], v[76:77], off offset:16
	global_load_dwordx4 v[92:95], v[74:75], off offset:2048
	global_load_dwordx4 v[88:91], v[74:75], off offset:2064
	s_nop 0
	global_load_dwordx4 v[76:79], v[72:73], off
	s_nop 0
	global_load_dwordx4 v[72:75], v[72:73], off offset:16
	v_mov_b32_e32 v131, v157
	s_waitcnt vmcnt(7)
	v_pk_add_f32 v[140:141], v[132:133], 1.0 op_sel_hi:[1,0]
	v_pk_add_f32 v[138:139], v[134:135], 1.0 op_sel_hi:[1,0]
	s_waitcnt vmcnt(6)
	v_pk_add_f32 v[136:137], v[142:143], 1.0 op_sel_hi:[1,0]
	v_pk_add_f32 v[134:135], v[144:145], 1.0 op_sel_hi:[1,0]
	s_waitcnt vmcnt(5)
	v_pk_add_f32 v[132:133], v[158:159], 1.0 op_sel_hi:[1,0]
	v_pk_add_f32 v[144:145], v[160:161], 1.0 op_sel_hi:[1,0]
	s_waitcnt vmcnt(0)
	v_pk_add_f32 v[142:143], v[162:163], 1.0 op_sel_hi:[1,0]
	v_pk_add_f32 v[146:147], v[164:165], 1.0 op_sel_hi:[1,0]
	s_branch .LBB0_1855
